# conv phase: next-unit tap loads go straight to their final registers with one incremented base address (no wait+select right behind the loads) unless the unit starts within 32 tokens of a sequence sta
# speedup vs baseline: 1.0175x; 1.0019x over previous
.LBB0_540:
	s_andn2_b64 vcc, exec, s[0:1]
	s_cbranch_vccnz .LBB0_542
	v_and_b32_e32 v15, 0x3ff0, v14
	v_cmp_lt_u32_e64 s[8:9], 31, v15
	s_and_b64 vcc, exec, s[8:9]
	s_cbranch_vccz .Lconv_slow
	v_subrev_u32_e32 v86, 30, v14
	v_ashrrev_i32_e32 v87, 31, v86
	v_lshlrev_b64 v[86:87], 10, v[86:87]
	v_lshl_add_u64 v[86:87], v[10:11], 0, v[86:87]
	v_mov_b32_e32 v88, 0x1000
	v_mov_b32_e32 v89, 0
	global_load_dword v55, v[86:87], off
	global_load_dword v56, v[86:87], off offset:1024
	global_load_dword v57, v[86:87], off offset:2048
	global_load_dword v58, v[86:87], off offset:3072
	v_lshl_add_u64 v[86:87], v[86:87], 0, v[88:89]
	global_load_dword v59, v[86:87], off
	global_load_dword v60, v[86:87], off offset:1024
	global_load_dword v61, v[86:87], off offset:2048
	global_load_dword v62, v[86:87], off offset:3072
	v_lshl_add_u64 v[86:87], v[86:87], 0, v[88:89]
	global_load_dword v63, v[86:87], off
	global_load_dword v64, v[86:87], off offset:1024
	global_load_dword v65, v[86:87], off offset:2048
	global_load_dword v66, v[86:87], off offset:3072
	v_lshl_add_u64 v[86:87], v[86:87], 0, v[88:89]
	global_load_dword v67, v[86:87], off
	global_load_dword v68, v[86:87], off offset:1024
	global_load_dword v69, v[86:87], off offset:2048
	global_load_dword v70, v[86:87], off offset:3072
	v_lshl_add_u64 v[86:87], v[86:87], 0, v[88:89]
	global_load_dword v71, v[86:87], off
	global_load_dword v72, v[86:87], off offset:1024
	global_load_dword v73, v[86:87], off offset:2048
	global_load_dword v74, v[86:87], off offset:3072
	v_lshl_add_u64 v[86:87], v[86:87], 0, v[88:89]
	global_load_dword v75, v[86:87], off
	global_load_dword v76, v[86:87], off offset:1024
	global_load_dword v77, v[86:87], off offset:2048
	global_load_dword v78, v[86:87], off offset:3072
	v_lshl_add_u64 v[86:87], v[86:87], 0, v[88:89]
	global_load_dword v79, v[86:87], off
	global_load_dword v80, v[86:87], off offset:1024
	global_load_dword v81, v[86:87], off offset:2048
	global_load_dword v82, v[86:87], off offset:3072
	v_lshl_add_u64 v[86:87], v[86:87], 0, v[88:89]
	global_load_dword v83, v[86:87], off
	global_load_dword v84, v[86:87], off offset:1024
	s_branch .LBB0_542
.Lconv_slow:
	v_and_b32_e32 v15, 0x3ff0, v14
	v_subrev_u32_e32 v55, 30, v14
	v_cmp_lt_u32_e32 vcc, 29, v15
	v_cmp_lt_u32_e64 s[8:9], 28, v15
	v_cmp_lt_u32_e64 s[10:11], 27, v15
	v_cndmask_b32_e32 v56, v14, v55, vcc
	v_subrev_u32_e32 v55, 29, v14
	v_cndmask_b32_e64 v58, v14, v55, s[8:9]
	v_subrev_u32_e32 v55, 28, v14
	v_cndmask_b32_e64 v60, v14, v55, s[10:11]
	v_subrev_u32_e32 v55, 27, v14
	v_cmp_lt_u32_e64 s[12:13], 26, v15
	v_cmp_lt_u32_e64 s[14:15], 25, v15
	v_cmp_lt_u32_e64 s[16:17], 24, v15
	v_cndmask_b32_e64 v62, v14, v55, s[12:13]
	v_subrev_u32_e32 v55, 26, v14
	v_cndmask_b32_e64 v64, v14, v55, s[14:15]
	v_subrev_u32_e32 v55, 25, v14
	v_cndmask_b32_e64 v66, v14, v55, s[16:17]
	v_subrev_u32_e32 v55, 24, v14
	v_cmp_lt_u32_e64 s[18:19], 23, v15
	v_cmp_lt_u32_e64 s[20:21], 22, v15
	v_ashrrev_i32_e32 v57, 31, v56
	v_cndmask_b32_e64 v68, v14, v55, s[18:19]
	v_subrev_u32_e32 v55, 23, v14
	v_cndmask_b32_e64 v70, v14, v55, s[20:21]
	v_lshlrev_b64 v[56:57], 10, v[56:57]
	v_ashrrev_i32_e32 v59, 31, v58
	v_ashrrev_i32_e32 v61, 31, v60
	v_ashrrev_i32_e32 v63, 31, v62
	v_ashrrev_i32_e32 v65, 31, v64
	v_ashrrev_i32_e32 v67, 31, v66
	v_ashrrev_i32_e32 v69, 31, v68
	v_ashrrev_i32_e32 v71, 31, v70
	v_lshl_add_u64 v[56:57], v[10:11], 0, v[56:57]
	v_lshlrev_b64 v[58:59], 10, v[58:59]
	v_lshlrev_b64 v[60:61], 10, v[60:61]
	v_lshlrev_b64 v[62:63], 10, v[62:63]
	v_lshlrev_b64 v[64:65], 10, v[64:65]
	v_lshlrev_b64 v[66:67], 10, v[66:67]
	v_lshlrev_b64 v[68:69], 10, v[68:69]
	v_lshlrev_b64 v[70:71], 10, v[70:71]
	v_lshl_add_u64 v[58:59], v[10:11], 0, v[58:59]
	v_lshl_add_u64 v[60:61], v[10:11], 0, v[60:61]
	v_lshl_add_u64 v[62:63], v[10:11], 0, v[62:63]
	v_lshl_add_u64 v[64:65], v[10:11], 0, v[64:65]
	v_lshl_add_u64 v[66:67], v[10:11], 0, v[66:67]
	v_lshl_add_u64 v[68:69], v[10:11], 0, v[68:69]
	v_lshl_add_u64 v[70:71], v[10:11], 0, v[70:71]
	global_load_dword v55, v[56:57], off
	global_load_dword v72, v[58:59], off
	global_load_dword v73, v[60:61], off
	global_load_dword v74, v[62:63], off
	global_load_dword v75, v[64:65], off
	global_load_dword v76, v[66:67], off
	global_load_dword v77, v[68:69], off
	global_load_dword v78, v[70:71], off
	v_subrev_u32_e32 v56, 22, v14
	v_cmp_lt_u32_e64 s[22:23], 21, v15
	v_subrev_u32_e32 v58, 21, v14
	v_cmp_lt_u32_e64 s[24:25], 20, v15
	v_cndmask_b32_e64 v56, v14, v56, s[22:23]
	v_subrev_u32_e32 v60, 20, v14
	v_cmp_lt_u32_e64 s[26:27], 19, v15
	v_subrev_u32_e32 v62, 19, v14
	v_cmp_lt_u32_e64 s[28:29], 18, v15
	v_subrev_u32_e32 v64, 18, v14
	v_cmp_lt_u32_e64 s[30:31], 17, v15
	v_subrev_u32_e32 v66, 17, v14
	v_cmp_lt_u32_e64 s[36:37], 16, v15
	v_add_u32_e32 v68, -16, v14
	v_cmp_eq_u32_e64 s[34:35], 0, v15
	v_add_u32_e32 v70, -15, v14
	v_ashrrev_i32_e32 v57, 31, v56
	v_cndmask_b32_e64 v58, v14, v58, s[24:25]
	v_cndmask_b32_e64 v60, v14, v60, s[26:27]
	v_cndmask_b32_e64 v62, v14, v62, s[28:29]
	v_cndmask_b32_e64 v64, v14, v64, s[30:31]
	v_cndmask_b32_e64 v66, v14, v66, s[36:37]
	v_cndmask_b32_e64 v68, v68, v14, s[34:35]
	v_cndmask_b32_e64 v70, v70, v14, s[34:35]
	v_lshlrev_b64 v[56:57], 10, v[56:57]
	v_ashrrev_i32_e32 v59, 31, v58
	v_ashrrev_i32_e32 v61, 31, v60
	v_ashrrev_i32_e32 v63, 31, v62
	v_ashrrev_i32_e32 v65, 31, v64
	v_ashrrev_i32_e32 v67, 31, v66
	v_ashrrev_i32_e32 v69, 31, v68
	v_ashrrev_i32_e32 v71, 31, v70
	v_lshl_add_u64 v[56:57], v[10:11], 0, v[56:57]
	v_lshlrev_b64 v[58:59], 10, v[58:59]
	v_lshlrev_b64 v[60:61], 10, v[60:61]
	v_lshlrev_b64 v[62:63], 10, v[62:63]
	v_lshlrev_b64 v[64:65], 10, v[64:65]
	v_lshlrev_b64 v[66:67], 10, v[66:67]
	v_lshlrev_b64 v[68:69], 10, v[68:69]
	v_lshlrev_b64 v[70:71], 10, v[70:71]
	v_lshl_add_u64 v[58:59], v[10:11], 0, v[58:59]
	v_lshl_add_u64 v[60:61], v[10:11], 0, v[60:61]
	v_lshl_add_u64 v[62:63], v[10:11], 0, v[62:63]
	v_lshl_add_u64 v[64:65], v[10:11], 0, v[64:65]
	v_lshl_add_u64 v[66:67], v[10:11], 0, v[66:67]
	v_lshl_add_u64 v[68:69], v[10:11], 0, v[68:69]
	v_lshl_add_u64 v[70:71], v[10:11], 0, v[70:71]
	global_load_dword v79, v[56:57], off
	global_load_dword v80, v[58:59], off
	global_load_dword v81, v[60:61], off
	global_load_dword v82, v[62:63], off
	global_load_dword v83, v[64:65], off
	global_load_dword v84, v[66:67], off
	global_load_dword v85, v[68:69], off
	global_load_dword v86, v[70:71], off
	v_add_u32_e32 v56, -14, v14
	v_cndmask_b32_e64 v56, v56, v14, s[34:35]
	v_add_u32_e32 v58, -13, v14
	v_add_u32_e32 v60, -12, v14
	v_add_u32_e32 v62, -11, v14
	v_add_u32_e32 v64, -10, v14
	v_add_u32_e32 v66, -9, v14
	v_add_u32_e32 v68, -8, v14
	v_add_u32_e32 v70, -7, v14
	v_ashrrev_i32_e32 v57, 31, v56
	v_cndmask_b32_e64 v58, v58, v14, s[34:35]
	v_cndmask_b32_e64 v60, v60, v14, s[34:35]
	v_cndmask_b32_e64 v62, v62, v14, s[34:35]
	v_cndmask_b32_e64 v64, v64, v14, s[34:35]
	v_cndmask_b32_e64 v66, v66, v14, s[34:35]
	v_cndmask_b32_e64 v68, v68, v14, s[34:35]
	v_cndmask_b32_e64 v70, v70, v14, s[34:35]
	v_lshlrev_b64 v[56:57], 10, v[56:57]
	v_ashrrev_i32_e32 v59, 31, v58
	v_ashrrev_i32_e32 v61, 31, v60
	v_ashrrev_i32_e32 v63, 31, v62
	v_ashrrev_i32_e32 v65, 31, v64
	v_ashrrev_i32_e32 v67, 31, v66
	v_ashrrev_i32_e32 v69, 31, v68
	v_ashrrev_i32_e32 v71, 31, v70
	v_lshl_add_u64 v[56:57], v[10:11], 0, v[56:57]
	v_lshlrev_b64 v[58:59], 10, v[58:59]
	v_lshlrev_b64 v[60:61], 10, v[60:61]
	v_lshlrev_b64 v[62:63], 10, v[62:63]
	v_lshlrev_b64 v[64:65], 10, v[64:65]
	v_lshlrev_b64 v[66:67], 10, v[66:67]
	v_lshlrev_b64 v[68:69], 10, v[68:69]
	v_lshlrev_b64 v[70:71], 10, v[70:71]
	v_lshl_add_u64 v[58:59], v[10:11], 0, v[58:59]
	v_lshl_add_u64 v[60:61], v[10:11], 0, v[60:61]
	v_lshl_add_u64 v[62:63], v[10:11], 0, v[62:63]
	v_lshl_add_u64 v[64:65], v[10:11], 0, v[64:65]
	v_lshl_add_u64 v[66:67], v[10:11], 0, v[66:67]
	v_lshl_add_u64 v[68:69], v[10:11], 0, v[68:69]
	v_lshl_add_u64 v[70:71], v[10:11], 0, v[70:71]
	global_load_dword v87, v[56:57], off
	global_load_dword v88, v[58:59], off
	global_load_dword v89, v[60:61], off
	global_load_dword v90, v[62:63], off
	global_load_dword v91, v[64:65], off
	global_load_dword v92, v[66:67], off
	global_load_dword v93, v[68:69], off
	global_load_dword v94, v[70:71], off
	v_add_u32_e32 v56, -6, v14
	v_cndmask_b32_e64 v56, v56, v14, s[34:35]
	v_add_u32_e32 v58, -5, v14
	v_add_u32_e32 v60, -4, v14
	v_add_u32_e32 v62, -3, v14
	v_add_u32_e32 v64, -2, v14
	v_cmp_ne_u32_e64 s[0:1], 0, v15
	v_ashrrev_i32_e32 v57, 31, v56
	v_cndmask_b32_e64 v58, v58, v14, s[34:35]
	v_cndmask_b32_e64 v60, v60, v14, s[34:35]
	v_cndmask_b32_e64 v62, v62, v14, s[34:35]
	v_cndmask_b32_e64 v64, v64, v14, s[34:35]
	v_subbrev_co_u32_e64 v66, s[38:39], 0, v14, s[0:1]
	v_lshlrev_b64 v[56:57], 10, v[56:57]
	v_ashrrev_i32_e32 v59, 31, v58
	v_ashrrev_i32_e32 v61, 31, v60
	v_ashrrev_i32_e32 v63, 31, v62
	v_ashrrev_i32_e32 v65, 31, v64
	v_ashrrev_i32_e32 v67, 31, v66
	v_lshl_add_u64 v[56:57], v[10:11], 0, v[56:57]
	v_lshlrev_b64 v[58:59], 10, v[58:59]
	v_lshlrev_b64 v[60:61], 10, v[60:61]
	v_lshlrev_b64 v[62:63], 10, v[62:63]
	v_lshlrev_b64 v[64:65], 10, v[64:65]
	v_lshlrev_b64 v[66:67], 10, v[66:67]
	v_lshl_add_u64 v[58:59], v[10:11], 0, v[58:59]
	v_lshl_add_u64 v[60:61], v[10:11], 0, v[60:61]
	v_lshl_add_u64 v[62:63], v[10:11], 0, v[62:63]
	v_lshl_add_u64 v[64:65], v[10:11], 0, v[64:65]
	v_lshl_add_u64 v[66:67], v[10:11], 0, v[66:67]
	global_load_dword v15, v[56:57], off
	global_load_dword v95, v[58:59], off
	global_load_dword v96, v[60:61], off
	global_load_dword v97, v[62:63], off
	global_load_dword v98, v[64:65], off
	global_load_dword v99, v[66:67], off
	s_waitcnt vmcnt(29)
	v_cndmask_b32_e32 v55, 0, v55, vcc
	s_waitcnt vmcnt(28)
	v_cndmask_b32_e64 v56, 0, v72, s[8:9]
	s_waitcnt vmcnt(27)
	v_cndmask_b32_e64 v57, 0, v73, s[10:11]
	s_waitcnt vmcnt(26)
	v_cndmask_b32_e64 v58, 0, v74, s[12:13]
	s_waitcnt vmcnt(25)
	v_cndmask_b32_e64 v59, 0, v75, s[14:15]
	s_waitcnt vmcnt(24)
	v_cndmask_b32_e64 v60, 0, v76, s[16:17]
	s_waitcnt vmcnt(23)
	v_cndmask_b32_e64 v61, 0, v77, s[18:19]
	s_waitcnt vmcnt(22)
	v_cndmask_b32_e64 v62, 0, v78, s[20:21]
	s_waitcnt vmcnt(21)
	v_cndmask_b32_e64 v63, 0, v79, s[22:23]
	s_waitcnt vmcnt(20)
	v_cndmask_b32_e64 v64, 0, v80, s[24:25]
	s_waitcnt vmcnt(19)
	v_cndmask_b32_e64 v65, 0, v81, s[26:27]
	s_waitcnt vmcnt(18)
	v_cndmask_b32_e64 v66, 0, v82, s[28:29]
	s_waitcnt vmcnt(17)
	v_cndmask_b32_e64 v67, 0, v83, s[30:31]
	s_waitcnt vmcnt(16)
	v_cndmask_b32_e64 v68, 0, v84, s[36:37]
	s_waitcnt vmcnt(15)
	v_cndmask_b32_e64 v69, v85, 0, s[34:35]
	s_waitcnt vmcnt(14)
	v_cndmask_b32_e64 v70, v86, 0, s[34:35]
	s_waitcnt vmcnt(13)
	v_cndmask_b32_e64 v71, v87, 0, s[34:35]
	s_waitcnt vmcnt(12)
	v_cndmask_b32_e64 v72, v88, 0, s[34:35]
	s_waitcnt vmcnt(11)
	v_cndmask_b32_e64 v73, v89, 0, s[34:35]
	s_waitcnt vmcnt(10)
	v_cndmask_b32_e64 v74, v90, 0, s[34:35]
	s_waitcnt vmcnt(9)
	v_cndmask_b32_e64 v75, v91, 0, s[34:35]
	s_waitcnt vmcnt(8)
	v_cndmask_b32_e64 v76, v92, 0, s[34:35]
	s_waitcnt vmcnt(7)
	v_cndmask_b32_e64 v77, v93, 0, s[34:35]
	s_waitcnt vmcnt(6)
	v_cndmask_b32_e64 v78, v94, 0, s[34:35]
	s_waitcnt vmcnt(5)
	v_cndmask_b32_e64 v79, v15, 0, s[34:35]
	s_waitcnt vmcnt(4)
	v_cndmask_b32_e64 v80, v95, 0, s[34:35]
	s_waitcnt vmcnt(3)
	v_cndmask_b32_e64 v81, v96, 0, s[34:35]
	s_waitcnt vmcnt(2)
	v_cndmask_b32_e64 v82, v97, 0, s[34:35]
	s_waitcnt vmcnt(1)
	v_cndmask_b32_e64 v83, v98, 0, s[34:35]
	s_waitcnt vmcnt(0)
	v_cndmask_b32_e64 v84, 0, v99, s[0:1]
